# banded mode-2 item remap: the 8 waves of a workgroup take the 4 q-heads of one kv head x 2 adjacent query blocks (shared K/V tiles -> L1 hits)
# baseline (speedup 1.0000x reference)
.LBB0_901:
	s_bfe_u32 s4, s47, 0x60003
	s_lshl_b32 s4, s4, 6
	s_bfe_u32 s50, s47, 0x10002
	s_lshl_b32 s50, s50, 5
	s_or_b32 s50, s50, s4
	s_add_i32 s5, s50, 0x9f
	s_add_i32 s4, s50, 0xffffff80
	s_lshr_b32 s5, s5, 6
	s_bfe_u32 s48, s47, 0x20009
	s_lshl_b32 s48, s48, 2
	s_and_b32 s6, s47, 3
	s_or_b32 s48, s48, s6
	s_ashr_i32 s49, s47, 11
	s_ashr_i32 s4, s4, 6
	s_add_i32 s5, s5, 1
	s_cmpk_lt_u32 s50, 0xf61
	s_cselect_b32 s51, s5, 64
	v_mov_b32_e32 v49, 0
	s_cmp_ge_i32 s4, s51
	v_mov_b32_e32 v48, 0
	v_mov_b32_e32 v47, 0
	v_mov_b32_e32 v46, 0
	v_mov_b32_e32 v45, 0
	v_mov_b32_e32 v44, 0
	v_mov_b32_e32 v43, 0
	v_mov_b32_e32 v42, 0
	v_mov_b32_e32 v41, 0
	v_mov_b32_e32 v40, 0
	v_mov_b32_e32 v39, 0
	v_mov_b32_e32 v38, 0
	v_mov_b32_e32 v37, 0
	v_mov_b32_e32 v36, 0
	v_mov_b32_e32 v35, 0
	v_mov_b32_e32 v34, 0
	v_mov_b32_e32 v65, 0
	v_mov_b32_e32 v64, 0
	v_mov_b32_e32 v63, 0
	v_mov_b32_e32 v62, 0
	v_mov_b32_e32 v61, 0
	v_mov_b32_e32 v60, 0
	v_mov_b32_e32 v59, 0
	v_mov_b32_e32 v58, 0
	v_mov_b32_e32 v57, 0
	v_mov_b32_e32 v56, 0
	v_mov_b32_e32 v55, 0
	v_mov_b32_e32 v54, 0
	v_mov_b32_e32 v53, 0
	v_mov_b32_e32 v52, 0
	v_mov_b32_e32 v51, 0
	v_mov_b32_e32 v50, 0
	v_mov_b32_e32 v214, v179
	s_cbranch_scc1 .LBB0_900
	s_mov_b32 s5, s50
	v_subrev_u32_e32 v212, s5, v211
	s_lshl_b32 s5, s49, 4
	s_or_b32 s6, s5, s48
	s_ashr_i32 s7, s6, 31
	s_lshl_b64 s[6:7], s[6:7], 12
	s_or_b32 s5, s6, s50
	v_mov_b32_e32 v1, s7
	v_or_b32_e32 v0, s5, v178
	s_lshr_b32 s5, s48, 2
	s_lshl_b32 s6, s49, 2
	v_lshlrev_b64 v[0:1], 7, v[0:1]
	s_or_b32 s6, s5, s6
	s_not_b32 s5, s48
	v_lshl_add_u64 v[0:1], v[180:181], 0, v[0:1]
	s_lshl_b32 s5, s5, 3
	global_load_dwordx4 v[98:101], v[0:1], off
	global_load_dwordx4 v[102:105], v[0:1], off offset:32
	global_load_dwordx4 v[106:109], v[0:1], off offset:64
	global_load_dwordx4 v[110:113], v[0:1], off offset:96
	v_cvt_f32_i32_e32 v0, s5
	s_ashr_i32 s7, s6, 31
	s_lshl_b64 s[6:7], s[6:7], 19
	v_lshl_add_u64 v[204:205], v[182:183], 0, s[6:7]
	v_mul_f32_e32 v1, 0x3d800000, v0
	v_cmp_gt_f32_e32 vcc, s8, v1
	v_lshl_add_u64 v[206:207], v[184:185], 0, s[6:7]
	s_and_b64 s[6:7], vcc, exec
	v_cndmask_b32_e32 v1, 0, v241, vcc
	v_fmac_f32_e32 v1, 0x3d800000, v0
	v_exp_f32_e32 v0, v1
	s_cselect_b32 s5, 0xffffffc0, 0
	s_mov_b64 s[6:7], s[58:59]
	s_mov_b32 s8, s65
	v_ldexp_f32 v0, v0, s5
	s_lshl_b32 s5, s48, 2
	v_mul_f32_e32 v4, 0x3fb8aa3b, v0
	v_mov_b32_e32 v0, s5
	s_mov_b32 s5, s64
	s_mov_b32 s9, s57
	v_readlane_b32 s52, v253, 2
	v_readlane_b32 s56, v253, 6
	v_readlane_b32 s57, v253, 7
	s_max_i32 s52, s4, 0
	s_lshl_b32 s16, s52, 13
	v_mov_b32_e32 v46, v33
	v_mov_b32_e32 v47, v33
	v_mov_b32_e32 v32, v33
	global_load_dword v0, v0, s[56:57]
	v_lshl_add_u64 v[6:7], v[204:205], 0, s[16:17]
	v_add_co_u32_e32 v8, vcc, s79, v6
	v_mov_b32_e32 v34, v33
	v_mov_b32_e32 v35, v33
	v_addc_co_u32_e32 v9, vcc, 0, v7, vcc
	global_load_dwordx4 v[114:117], v[8:9], off offset:3072
	global_load_dwordx4 v[118:121], v[8:9], off offset:2048
	global_load_dwordx4 v[122:125], v[8:9], off offset:1024
	global_load_dwordx4 v[126:129], v[8:9], off
	global_load_dwordx4 v[130:133], v[6:7], off offset:3072
	global_load_dwordx4 v[134:137], v[6:7], off offset:2048
	global_load_dwordx4 v[138:141], v[6:7], off offset:1024
	global_load_dwordx4 v[142:145], v[6:7], off
	v_lshl_add_u64 v[10:11], v[206:207], 0, s[16:17]
	global_load_dwordx4 v[174:177], v[10:11], off offset:-4096
	global_load_dwordx4 v[170:173], v[10:11], off offset:-3072
	global_load_dwordx4 v[166:169], v[10:11], off offset:-2048
	global_load_dwordx4 v[162:165], v[10:11], off offset:-1024
	global_load_dwordx4 v[158:161], v[10:11], off
	global_load_dwordx4 v[154:157], v[10:11], off offset:1024
	global_load_dwordx4 v[150:153], v[10:11], off offset:2048
	global_load_dwordx4 v[146:149], v[10:11], off offset:3072
	v_mov_b32_e32 v36, v33
	v_mov_b32_e32 v37, v33
	v_mov_b32_e32 v38, v33
	v_mov_b32_e32 v39, v33
	v_mov_b32_e32 v40, v33
	v_mov_b32_e32 v41, v33
	v_mov_b32_e32 v42, v33
	v_mov_b32_e32 v43, v33
	v_mov_b32_e32 v44, v33
	v_mov_b32_e32 v45, v33
	v_mov_b64_e32 v[64:65], v[46:47]
	v_readlane_b32 s53, v253, 3
	v_readlane_b32 s54, v253, 4
	v_readlane_b32 s55, v253, 5
	v_readlane_b32 s58, v253, 8
	v_readlane_b32 s59, v253, 9
	v_readlane_b32 s60, v253, 10
	v_readlane_b32 s61, v253, 11
	v_readlane_b32 s62, v253, 12
	v_readlane_b32 s63, v253, 13
	v_readlane_b32 s64, v253, 14
	v_readlane_b32 s65, v253, 15
	v_readlane_b32 s66, v253, 16
	v_readlane_b32 s67, v253, 17
	v_readfirstlane_b32 s38, v4
	v_mov_b64_e32 v[62:63], v[44:45]
	v_mov_b64_e32 v[60:61], v[42:43]
	v_mov_b64_e32 v[58:59], v[40:41]
	v_mov_b64_e32 v[56:57], v[38:39]
	v_mov_b64_e32 v[54:55], v[36:37]
	v_mov_b64_e32 v[52:53], v[34:35]
	v_mov_b64_e32 v[50:51], v[32:33]
	v_mov_b64_e32 v[48:49], v[46:47]
	s_mov_b32 s65, s8
	s_mov_b32 s64, s5
	s_mov_b64 s[58:59], s[6:7]
	s_mov_b32 s57, s9
	s_add_i32 s53, s50, 0x42
	s_add_i32 s54, s50, 0xffffff9e
	s_mov_b32 s39, s38
	s_mov_b32 s55, s38
	s_mov_b32 s60, s38
	s_mov_b32 s61, s38
	s_mov_b32 s62, s38
	s_mov_b32 s63, s38
	s_mov_b32 s66, s38
	s_mov_b32 s67, s38
	s_mov_b32 s69, s38
	s_mov_b32 s70, s38
	s_mov_b32 s71, s38
	s_mov_b32 s80, s38
	s_mov_b32 s81, s38
	s_mov_b32 s82, s38
	s_mov_b32 s83, s38
	s_mov_b32 s84, s38
	s_mov_b32 s85, s38
	s_mov_b32 s86, s38
	s_mov_b32 s87, s38
	s_mov_b32 s88, s38
	s_mov_b32 s89, s38
	s_mov_b32 s93, s38
	s_mov_b32 s94, s38
	s_mov_b32 s95, s38
	s_mov_b32 s96, s38
	s_mov_b32 s97, s38
	s_mov_b32 s4, s38
	s_mov_b32 s5, s38
	s_mov_b32 s6, s38
	s_mov_b32 s7, s38
	s_mov_b32 s8, s38
	s_lshl_b32 s9, s52, 6
	s_mov_b64 s[40:41], s[16:17]
	v_mov_b64_e32 v[46:47], v[44:45]
	v_mov_b64_e32 v[44:45], v[42:43]
	v_mov_b64_e32 v[42:43], v[40:41]
	v_mov_b64_e32 v[40:41], v[38:39]
	v_mov_b64_e32 v[38:39], v[36:37]
	s_waitcnt vmcnt(16)
	v_mul_f32_e32 v213, 0x3fb8aa3b, v0
	v_mov_b64_e32 v[36:37], v[34:35]
	v_mov_b64_e32 v[34:35], v[32:33]
	v_mov_b32_e32 v214, v179
	s_branch .LBB0_904
